# NORM GEMM loops rebuilt: next-tile loads issued right after each LDS write, row sum-of-squares via v_dot2c_f32_bf16 on the bf16 A tile (f32 accumulate), MFMA phase software-pipelined ds_reads
# speedup vs baseline: 1.6229x; 1.0332x over previous
.LBB0_104:
	s_waitcnt lgkmcnt(0)
	s_barrier
	s_waitcnt vmcnt(11)
	ds_write_b128 v243, v[160:163] offset:36864
	v_add_u32_e32 v188, s2, v200
	v_add_u32_e32 v188, 0x40, v188
	v_lshl_add_u64 v[160:161], v[188:189], 1, s[24:25]
	global_load_dwordx4 v[160:163], v[160:161], off
	s_waitcnt vmcnt(11)
	ds_write_b128 v243, v[164:167] offset:41472
	v_add_u32_e32 v188, s2, v200
	v_add_u32_e32 v188, 0x8040, v188
	v_lshl_add_u64 v[164:165], v[188:189], 1, s[24:25]
	global_load_dwordx4 v[164:167], v[164:165], off
	s_waitcnt vmcnt(11)
	ds_write_b128 v243, v[168:171] offset:46080
	v_add_u32_e32 v188, s2, v200
	v_add_u32_e32 v188, 0x10040, v188
	v_lshl_add_u64 v[168:169], v[188:189], 1, s[24:25]
	global_load_dwordx4 v[168:171], v[168:169], off
	s_waitcnt vmcnt(11)
	ds_write_b128 v243, v[172:175] offset:50688
	v_add_u32_e32 v188, s2, v200
	v_add_u32_e32 v188, 0x18040, v188
	v_lshl_add_u64 v[172:173], v[188:189], 1, s[24:25]
	global_load_dwordx4 v[172:175], v[172:173], off
	s_waitcnt vmcnt(11)
	ds_write_b128 v243, v[156:159]
	v_dot2c_f32_bf16_e32 v197, v156, v156
	v_dot2c_f32_bf16_e32 v197, v157, v157
	v_dot2c_f32_bf16_e32 v197, v158, v158
	v_dot2c_f32_bf16_e32 v197, v159, v159
	v_add_u32_e32 v188, s2, v198
	v_add_u32_e32 v188, 0x40, v188
	v_lshl_add_u64 v[156:157], v[188:189], 1, s[36:37]
	global_load_dwordx4 v[156:159], v[156:157], off
	s_waitcnt vmcnt(11)
	ds_write_b128 v243, v[152:155] offset:4608
	v_dot2c_f32_bf16_e32 v196, v152, v152
	v_dot2c_f32_bf16_e32 v196, v153, v153
	v_dot2c_f32_bf16_e32 v196, v154, v154
	v_dot2c_f32_bf16_e32 v196, v155, v155
	v_add_u32_e32 v188, s2, v198
	v_add_u32_e32 v188, 0x8040, v188
	v_lshl_add_u64 v[152:153], v[188:189], 1, s[36:37]
	global_load_dwordx4 v[152:155], v[152:153], off
	s_waitcnt vmcnt(11)
	ds_write_b128 v243, v[148:151] offset:9216
	v_dot2c_f32_bf16_e32 v195, v148, v148
	v_dot2c_f32_bf16_e32 v195, v149, v149
	v_dot2c_f32_bf16_e32 v195, v150, v150
	v_dot2c_f32_bf16_e32 v195, v151, v151
	v_add_u32_e32 v188, s2, v198
	v_add_u32_e32 v188, 0x10040, v188
	v_lshl_add_u64 v[148:149], v[188:189], 1, s[36:37]
	global_load_dwordx4 v[148:151], v[148:149], off
	s_waitcnt vmcnt(11)
	ds_write_b128 v243, v[144:147] offset:13824
	v_dot2c_f32_bf16_e32 v194, v144, v144
	v_dot2c_f32_bf16_e32 v194, v145, v145
	v_dot2c_f32_bf16_e32 v194, v146, v146
	v_dot2c_f32_bf16_e32 v194, v147, v147
	v_add_u32_e32 v188, s2, v198
	v_add_u32_e32 v188, 0x18040, v188
	v_lshl_add_u64 v[144:145], v[188:189], 1, s[36:37]
	global_load_dwordx4 v[144:147], v[144:145], off
	s_waitcnt vmcnt(11)
	ds_write_b128 v243, v[140:143] offset:18432
	v_dot2c_f32_bf16_e32 v193, v140, v140
	v_dot2c_f32_bf16_e32 v193, v141, v141
	v_dot2c_f32_bf16_e32 v193, v142, v142
	v_dot2c_f32_bf16_e32 v193, v143, v143
	v_add_u32_e32 v188, s2, v198
	v_add_u32_e32 v188, 0x20040, v188
	v_lshl_add_u64 v[140:141], v[188:189], 1, s[36:37]
	global_load_dwordx4 v[140:143], v[140:141], off
	s_waitcnt vmcnt(11)
	ds_write_b128 v243, v[136:139] offset:23040
	v_dot2c_f32_bf16_e32 v192, v136, v136
	v_dot2c_f32_bf16_e32 v192, v137, v137
	v_dot2c_f32_bf16_e32 v192, v138, v138
	v_dot2c_f32_bf16_e32 v192, v139, v139
	v_add_u32_e32 v188, s2, v198
	v_add_u32_e32 v188, 0x28040, v188
	v_lshl_add_u64 v[136:137], v[188:189], 1, s[36:37]
	global_load_dwordx4 v[136:139], v[136:137], off
	s_waitcnt vmcnt(11)
	ds_write_b128 v243, v[132:135] offset:27648
	v_dot2c_f32_bf16_e32 v191, v132, v132
	v_dot2c_f32_bf16_e32 v191, v133, v133
	v_dot2c_f32_bf16_e32 v191, v134, v134
	v_dot2c_f32_bf16_e32 v191, v135, v135
	v_add_u32_e32 v188, s2, v198
	v_add_u32_e32 v188, 0x30040, v188
	v_lshl_add_u64 v[132:133], v[188:189], 1, s[36:37]
	global_load_dwordx4 v[132:135], v[132:133], off
	s_waitcnt vmcnt(11)
	ds_write_b128 v243, v[128:131] offset:32256
	v_dot2c_f32_bf16_e32 v190, v128, v128
	v_dot2c_f32_bf16_e32 v190, v129, v129
	v_dot2c_f32_bf16_e32 v190, v130, v130
	v_dot2c_f32_bf16_e32 v190, v131, v131
	v_add_u32_e32 v188, s2, v198
	v_add_u32_e32 v188, 0x38040, v188
	v_lshl_add_u64 v[128:129], v[188:189], 1, s[36:37]
	global_load_dwordx4 v[128:131], v[128:129], off
	s_waitcnt lgkmcnt(0)
	s_barrier
	ds_read_b128 v[244:247], v242 offset:36864
	ds_read_b128 v[184:187], v242 offset:41472
	ds_read_b128 v[248:251], v201
	ds_read_b128 v[232:235], v201 offset:4608
	s_waitcnt lgkmcnt(1)
	v_mfma_f32_32x32x16_bf16 v[112:127], v[248:251], v[244:247], v[112:127]
	v_mfma_f32_32x32x16_bf16 v[96:111], v[248:251], v[184:187], v[96:111]
	ds_read_b128 v[248:251], v201 offset:9216
	s_waitcnt lgkmcnt(1)
	v_mfma_f32_32x32x16_bf16 v[80:95], v[232:235], v[244:247], v[80:95]
	v_mfma_f32_32x32x16_bf16 v[64:79], v[232:235], v[184:187], v[64:79]
	ds_read_b128 v[232:235], v199
	ds_read_b128 v[176:179], v242 offset:36896
	ds_read_b128 v[180:183], v242 offset:41504
	s_waitcnt lgkmcnt(3)
	v_mfma_f32_32x32x16_bf16 v[48:63], v[248:251], v[244:247], v[48:63]
	v_mfma_f32_32x32x16_bf16 v[32:47], v[248:251], v[184:187], v[32:47]
	ds_read_b128 v[248:251], v201 offset:32
	s_waitcnt lgkmcnt(3)
	v_mfma_f32_32x32x16_bf16 v[16:31], v[232:235], v[244:247], v[16:31]
	v_mfma_f32_32x32x16_bf16 v[0:15], v[232:235], v[184:187], v[0:15]
	ds_read_b128 v[232:235], v201 offset:4640
	s_waitcnt lgkmcnt(1)
	v_mfma_f32_32x32x16_bf16 v[112:127], v[248:251], v[176:179], v[112:127]
	v_mfma_f32_32x32x16_bf16 v[96:111], v[248:251], v[180:183], v[96:111]
	ds_read_b128 v[248:251], v201 offset:9248
	s_waitcnt lgkmcnt(1)
	v_mfma_f32_32x32x16_bf16 v[80:95], v[232:235], v[176:179], v[80:95]
	v_mfma_f32_32x32x16_bf16 v[64:79], v[232:235], v[180:183], v[64:79]
	ds_read_b128 v[232:235], v199 offset:32
	ds_read_b128 v[244:247], v242 offset:36928
	ds_read_b128 v[184:187], v242 offset:41536
	s_waitcnt lgkmcnt(3)
; template <bool NORM, bool DEEP, int MTW, int KSEG, class HOOK>
; DI void gemm_core_h(const bfu* __restrict__ A, int lda, const bfu* __restrict__ Bt, int ldb, int K, int m0, int n0,
;                     f32x16 (&acc)[MTW][2], char* smem, HOOK hook) {
;     ...
;   if (DEEP) {
;     for (int kt = 0; kt < nk; kt += 2) {
;       GEMM_STEP(ra0, rb0, kt, 2)
;       GEMM_STEP(ra1, rb1, kt + 1, 2)
;     }
;   } else {
;     for (int kt = 0; kt < nk; ++kt) {
;       GEMM_STEP(ra0, rb0, kt, 1)
	v_mfma_f32_32x32x16_bf16 v[48:63], v[248:251], v[176:179], v[48:63]
	v_mfma_f32_32x32x16_bf16 v[32:47], v[248:251], v[180:183], v[32:47]
	ds_read_b128 v[248:251], v201 offset:64
	s_waitcnt lgkmcnt(3)
	v_mfma_f32_32x32x16_bf16 v[16:31], v[232:235], v[176:179], v[16:31]
	v_mfma_f32_32x32x16_bf16 v[0:15], v[232:235], v[180:183], v[0:15]
	ds_read_b128 v[232:235], v201 offset:4672
	s_waitcnt lgkmcnt(1)
	v_mfma_f32_32x32x16_bf16 v[112:127], v[248:251], v[244:247], v[112:127]
	v_mfma_f32_32x32x16_bf16 v[96:111], v[248:251], v[184:187], v[96:111]
	ds_read_b128 v[248:251], v201 offset:9280
	s_waitcnt lgkmcnt(1)
	v_mfma_f32_32x32x16_bf16 v[80:95], v[232:235], v[244:247], v[80:95]
	v_mfma_f32_32x32x16_bf16 v[64:79], v[232:235], v[184:187], v[64:79]
	ds_read_b128 v[232:235], v199 offset:64
	ds_read_b128 v[176:179], v242 offset:36960
	ds_read_b128 v[180:183], v242 offset:41568
	s_waitcnt lgkmcnt(3)
	v_mfma_f32_32x32x16_bf16 v[48:63], v[248:251], v[244:247], v[48:63]
	v_mfma_f32_32x32x16_bf16 v[32:47], v[248:251], v[184:187], v[32:47]
	ds_read_b128 v[248:251], v201 offset:96
	s_waitcnt lgkmcnt(3)
	v_mfma_f32_32x32x16_bf16 v[16:31], v[232:235], v[244:247], v[16:31]
	v_mfma_f32_32x32x16_bf16 v[0:15], v[232:235], v[184:187], v[0:15]
	ds_read_b128 v[232:235], v201 offset:4704
	s_waitcnt lgkmcnt(1)
	v_mfma_f32_32x32x16_bf16 v[112:127], v[248:251], v[176:179], v[112:127]
	v_mfma_f32_32x32x16_bf16 v[96:111], v[248:251], v[180:183], v[96:111]
	ds_read_b128 v[248:251], v201 offset:9312
	s_waitcnt lgkmcnt(1)
	v_mfma_f32_32x32x16_bf16 v[80:95], v[232:235], v[176:179], v[80:95]
	v_mfma_f32_32x32x16_bf16 v[64:79], v[232:235], v[180:183], v[64:79]
	ds_read_b128 v[232:235], v199 offset:96
	s_waitcnt lgkmcnt(1)
	v_mfma_f32_32x32x16_bf16 v[48:63], v[248:251], v[176:179], v[48:63]
	v_mfma_f32_32x32x16_bf16 v[32:47], v[248:251], v[180:183], v[32:47]
	s_waitcnt lgkmcnt(0)
	v_mfma_f32_32x32x16_bf16 v[16:31], v[232:235], v[176:179], v[16:31]
	v_mfma_f32_32x32x16_bf16 v[0:15], v[232:235], v[180:183], v[0:15]
	s_add_i32 s2, s2, 64
	s_cmpk_eq_i32 s2, 0x3c0
	s_cbranch_scc0 .LBB0_104
	s_waitcnt vmcnt(0)
	s_waitcnt lgkmcnt(0)
	s_barrier
	s_waitcnt vmcnt(11)
	ds_write_b128 v243, v[156:159]
	s_waitcnt vmcnt(10)
	ds_write_b128 v243, v[152:155] offset:4608
	s_waitcnt vmcnt(9)
	ds_write_b128 v243, v[148:151] offset:9216
	s_waitcnt vmcnt(8)
	ds_write_b128 v243, v[144:147] offset:13824
	s_waitcnt vmcnt(7)
	ds_write_b128 v243, v[140:143] offset:18432
	s_waitcnt vmcnt(6)
	ds_write_b128 v243, v[136:139] offset:23040
	s_waitcnt vmcnt(5)
	ds_write_b128 v243, v[132:135] offset:27648
	s_waitcnt vmcnt(4)
	ds_write_b128 v243, v[128:131] offset:32256
	s_waitcnt vmcnt(3)
	ds_write_b128 v243, v[160:163] offset:36864
	s_waitcnt vmcnt(2)
	ds_write_b128 v243, v[164:167] offset:41472
	s_waitcnt vmcnt(1)
	ds_write_b128 v243, v[168:171] offset:46080
	s_waitcnt vmcnt(0)
	ds_write_b128 v243, v[172:175] offset:50688
	s_waitcnt lgkmcnt(0)
	s_barrier
; template <bool NORM, bool DEEP, int MTW, int KSEG, class HOOK>
; DI void gemm_core_h(const bfu* __restrict__ A, int lda, const bfu* __restrict__ Bt, int ldb, int K, int m0, int n0,
;                     f32x16 (&acc)[MTW][2], char* smem, HOOK hook) {
;     ...
;   if (DEEP) {
;     for (int kt = 0; kt < nk; kt += 2) {
;       GEMM_STEP(ra0, rb0, kt, 2)
;       GEMM_STEP(ra1, rb1, kt + 1, 2)
;     }
;   } else {
;     for (int kt = 0; kt < nk; ++kt) {
;       GEMM_STEP(ra0, rb0, kt, 1)
;       if (KSEG > 0) { if (((kt + 1) % (KSEG > 0 ? KSEG : 1)) == 0) hook((kt + 1) / (KSEG > 0 ? KSEG : 1) - 1); }
;     }
;   }
;     ...
;   if (NORM) {
; #pragma unroll
;     for (int j = 0; j < NA; ++j) {
;       float v = ssq[j];
;       v += __shfl_xor(v, 1); v += __shfl_xor(v, 2); v += __shfl_xor(v, 4);
;       if (lkc == 0) rstd_s[lrow + 32 * j] = rsqrtf(v / (float)K + EPS);
;     }
	ds_read_b128 v[160:163], v201
	ds_read_b128 v[164:167], v242 offset:36864
	ds_read_b128 v[168:171], v242 offset:41472
	s_waitcnt lgkmcnt(1)
	v_mfma_f32_32x32x16_bf16 v[112:127], v[160:163], v[164:167], v[112:127]
	v_lshlrev_b32_e32 v176, 16, v156
	v_and_b32_e32 v156, 0xffff0000, v156
	v_mul_f32_e32 v156, v156, v156
	v_fmac_f32_e32 v156, v176, v176
	v_add_f32_e32 v156, v197, v156
	s_waitcnt lgkmcnt(0)
	v_mfma_f32_32x32x16_bf16 v[96:111], v[160:163], v[168:171], v[96:111]
	ds_read_b128 v[160:163], v201 offset:4608
	s_waitcnt lgkmcnt(0)
	v_mfma_f32_32x32x16_bf16 v[80:95], v[160:163], v[164:167], v[80:95]
	v_mfma_f32_32x32x16_bf16 v[64:79], v[160:163], v[168:171], v[64:79]
	ds_read_b128 v[160:163], v201 offset:9216
	s_waitcnt lgkmcnt(0)
	v_mfma_f32_32x32x16_bf16 v[48:63], v[160:163], v[164:167], v[48:63]
	v_mfma_f32_32x32x16_bf16 v[32:47], v[160:163], v[168:171], v[32:47]
	ds_read_b128 v[160:163], v199
	s_waitcnt lgkmcnt(0)
	v_mfma_f32_32x32x16_bf16 v[16:31], v[160:163], v[164:167], v[16:31]
	v_mfma_f32_32x32x16_bf16 v[0:15], v[160:163], v[168:171], v[0:15]
	ds_read_b128 v[160:163], v201 offset:32
	ds_read_b128 v[164:167], v242 offset:36896
	ds_read_b128 v[168:171], v242 offset:41504
	s_waitcnt lgkmcnt(1)
	v_mfma_f32_32x32x16_bf16 v[112:127], v[160:163], v[164:167], v[112:127]
	s_waitcnt lgkmcnt(0)
	v_mfma_f32_32x32x16_bf16 v[96:111], v[160:163], v[168:171], v[96:111]
	ds_read_b128 v[160:163], v201 offset:4640
	s_waitcnt lgkmcnt(0)
	v_mfma_f32_32x32x16_bf16 v[80:95], v[160:163], v[164:167], v[80:95]
	v_mfma_f32_32x32x16_bf16 v[64:79], v[160:163], v[168:171], v[64:79]
	ds_read_b128 v[160:163], v201 offset:9248
	s_waitcnt lgkmcnt(0)
	v_mfma_f32_32x32x16_bf16 v[48:63], v[160:163], v[164:167], v[48:63]
	v_mfma_f32_32x32x16_bf16 v[32:47], v[160:163], v[168:171], v[32:47]
	ds_read_b128 v[160:163], v199 offset:32
	s_waitcnt lgkmcnt(0)
	v_mfma_f32_32x32x16_bf16 v[16:31], v[160:163], v[164:167], v[16:31]
	v_mfma_f32_32x32x16_bf16 v[0:15], v[160:163], v[168:171], v[0:15]
	ds_read_b128 v[160:163], v201 offset:64
	ds_read_b128 v[164:167], v242 offset:36928
	ds_read_b128 v[168:171], v242 offset:41536
	s_waitcnt lgkmcnt(1)
	v_mfma_f32_32x32x16_bf16 v[112:127], v[160:163], v[164:167], v[112:127]
	s_waitcnt lgkmcnt(0)
	v_mfma_f32_32x32x16_bf16 v[96:111], v[160:163], v[168:171], v[96:111]
	ds_read_b128 v[160:163], v201 offset:4672
	s_waitcnt lgkmcnt(0)
	v_mfma_f32_32x32x16_bf16 v[80:95], v[160:163], v[164:167], v[80:95]
	v_mfma_f32_32x32x16_bf16 v[64:79], v[160:163], v[168:171], v[64:79]
	ds_read_b128 v[160:163], v201 offset:9280
	s_waitcnt lgkmcnt(0)
	v_mfma_f32_32x32x16_bf16 v[48:63], v[160:163], v[164:167], v[48:63]
	v_mfma_f32_32x32x16_bf16 v[32:47], v[160:163], v[168:171], v[32:47]
	ds_read_b128 v[160:163], v199 offset:64
	s_waitcnt lgkmcnt(0)
	v_mfma_f32_32x32x16_bf16 v[16:31], v[160:163], v[164:167], v[16:31]
	v_mfma_f32_32x32x16_bf16 v[0:15], v[160:163], v[168:171], v[0:15]
	ds_read_b128 v[164:167], v201 offset:96
	ds_read_b128 v[168:171], v242 offset:36960
	ds_read_b128 v[160:163], v242 offset:41568
	ds_read_b128 v[172:175], v201 offset:4704
	s_waitcnt lgkmcnt(2)
	v_mfma_f32_32x32x16_bf16 v[112:127], v[164:167], v[168:171], v[112:127]
	s_waitcnt lgkmcnt(1)
	v_mfma_f32_32x32x16_bf16 v[96:111], v[164:167], v[160:163], v[96:111]
	v_lshlrev_b32_e32 v164, 16, v157
	v_and_b32_e32 v157, 0xffff0000, v157
	v_mul_f32_e32 v157, v157, v157
	v_fmac_f32_e32 v157, v164, v164
	v_add_f32_e32 v156, v157, v156
	v_lshlrev_b32_e32 v157, 16, v158
	v_and_b32_e32 v158, 0xffff0000, v158
	v_mul_f32_e32 v158, v158, v158
	ds_read_b128 v[164:167], v201 offset:9312
	v_fmac_f32_e32 v158, v157, v157
	v_add_f32_e32 v156, v158, v156
	v_and_b32_e32 v158, 0xffff0000, v159
	v_lshlrev_b32_e32 v157, 16, v159
	v_mul_f32_e32 v158, v158, v158
	v_mbcnt_hi_u32_b32 v159, -1, v226
	v_fmac_f32_e32 v158, v157, v157
	v_and_b32_e32 v157, 64, v159
	v_add_f32_e32 v158, v158, v156
	v_xor_b32_e32 v156, 1, v159
	v_add_u32_e32 v176, 64, v157
	v_cmp_lt_i32_e64 s[2:3], v156, v176
	s_waitcnt lgkmcnt(1)
	v_mfma_f32_32x32x16_bf16 v[80:95], v[172:175], v[168:171], v[80:95]
	v_xor_b32_e32 v157, 2, v159
	v_cndmask_b32_e64 v156, v159, v156, s[2:3]
	v_lshlrev_b32_e32 v156, 2, v156
	v_cmp_lt_i32_e64 s[2:3], v157, v176
	s_nop 1
	v_cndmask_b32_e64 v157, v159, v157, s[2:3]
	v_mfma_f32_32x32x16_bf16 v[64:79], v[172:175], v[160:163], v[64:79]
	ds_read_b128 v[172:175], v199 offset:96
	v_lshlrev_b32_e32 v157, 2, v157
	s_waitcnt lgkmcnt(1)
	v_mfma_f32_32x32x16_bf16 v[48:63], v[164:167], v[168:171], v[48:63]
	v_mfma_f32_32x32x16_bf16 v[32:47], v[164:167], v[160:163], v[32:47]
	ds_bpermute_b32 v164, v156, v158
	v_xor_b32_e32 v165, 4, v159
	v_cmp_lt_i32_e64 s[2:3], v165, v176
	s_waitcnt lgkmcnt(0)
	v_add_f32_e32 v164, v158, v164
	ds_bpermute_b32 v166, v157, v164
	v_mfma_f32_32x32x16_bf16 v[16:31], v[172:175], v[168:171], v[16:31]
	v_cndmask_b32_e64 v158, v159, v165, s[2:3]
	v_lshlrev_b32_e32 v159, 2, v158
	v_cmp_eq_u32_e64 s[2:3], 0, v241
	s_waitcnt lgkmcnt(0)
	v_add_f32_e32 v164, v164, v166
	ds_bpermute_b32 v165, v159, v164
	v_lshlrev_b32_e32 v158, 2, v240
	v_mfma_f32_32x32x16_bf16 v[0:15], v[172:175], v[160:163], v[0:15]
	s_and_saveexec_b64 s[8:9], s[2:3]
	s_cbranch_execz .LBB0_107
	s_waitcnt lgkmcnt(0)
	v_add_f32_e32 v160, v164, v165
	v_fmamk_f32 v160, v160, 0x3a800000, v225
	s_mov_b32 s4, 0x800000
	v_mul_f32_e32 v161, 0x4b800000, v160
	v_cmp_gt_f32_e64 s[4:5], s4, v160
	s_nop 1
	v_cndmask_b32_e64 v160, v160, v161, s[4:5]
	v_rsq_f32_e32 v160, v160
	s_nop 0
	v_mul_f32_e32 v161, 0x45800000, v160
	v_cndmask_b32_e64 v160, v160, v161, s[4:5]
	ds_write_b32 v158, v160 offset:55296

.LBB0_782:
	s_waitcnt lgkmcnt(0)
	s_barrier
	v_readlane_b32 s52, v253, 32
	v_readlane_b32 s66, v253, 46
	v_readlane_b32 s67, v253, 47
	v_readlane_b32 s53, v253, 33
	v_readlane_b32 s54, v253, 34
	v_readlane_b32 s55, v253, 35
	v_readlane_b32 s56, v253, 36
	v_readlane_b32 s57, v253, 37
	v_readlane_b32 s58, v253, 38
	v_readlane_b32 s59, v253, 39
	v_readlane_b32 s60, v253, 40
	v_readlane_b32 s61, v253, 41
	v_readlane_b32 s62, v253, 42
	v_readlane_b32 s63, v253, 43
	v_readlane_b32 s64, v253, 44
	v_readlane_b32 s65, v253, 45
	s_waitcnt vmcnt(11)
	ds_write_b128 v212, v[160:163] offset:36864
	v_add_u32_e32 v188, s2, v204
	v_add_u32_e32 v188, 0x40, v188
	v_lshl_add_u64 v[160:161], v[188:189], 1, s[66:67]
	global_load_dwordx4 v[160:163], v[160:161], off
	s_waitcnt vmcnt(11)
	ds_write_b128 v212, v[164:167] offset:41472
	v_add_u32_e32 v188, s2, v204
	v_add_u32_e32 v188, 0x8040, v188
	v_lshl_add_u64 v[164:165], v[188:189], 1, s[66:67]
	global_load_dwordx4 v[164:167], v[164:165], off
	s_waitcnt vmcnt(11)
	ds_write_b128 v212, v[168:171] offset:46080
	v_add_u32_e32 v188, s2, v204
	v_add_u32_e32 v188, 0x10040, v188
	v_lshl_add_u64 v[168:169], v[188:189], 1, s[66:67]
	global_load_dwordx4 v[168:171], v[168:169], off
	s_waitcnt vmcnt(11)
	ds_write_b128 v212, v[172:175] offset:50688
	v_add_u32_e32 v188, s2, v204
	v_add_u32_e32 v188, 0x18040, v188
	v_lshl_add_u64 v[172:173], v[188:189], 1, s[66:67]
	global_load_dwordx4 v[172:175], v[172:173], off
	s_waitcnt vmcnt(11)
	ds_write_b128 v212, v[156:159]
	v_dot2c_f32_bf16_e32 v201, v156, v156
	v_dot2c_f32_bf16_e32 v201, v157, v157
	v_dot2c_f32_bf16_e32 v201, v158, v158
	v_dot2c_f32_bf16_e32 v201, v159, v159
	v_add_u32_e32 v188, s2, v202
	v_add_u32_e32 v188, 0x40, v188
	v_lshl_add_u64 v[156:157], v[188:189], 1, s[38:39]
	global_load_dwordx4 v[156:159], v[156:157], off
	s_waitcnt vmcnt(11)
	ds_write_b128 v212, v[152:155] offset:4608
	v_dot2c_f32_bf16_e32 v200, v152, v152
	v_dot2c_f32_bf16_e32 v200, v153, v153
	v_dot2c_f32_bf16_e32 v200, v154, v154
	v_dot2c_f32_bf16_e32 v200, v155, v155
	v_add_u32_e32 v188, s2, v202
	v_add_u32_e32 v188, 0x8040, v188
	v_lshl_add_u64 v[152:153], v[188:189], 1, s[38:39]
	global_load_dwordx4 v[152:155], v[152:153], off
	s_waitcnt vmcnt(11)
	ds_write_b128 v212, v[148:151] offset:9216
	v_dot2c_f32_bf16_e32 v199, v148, v148
	v_dot2c_f32_bf16_e32 v199, v149, v149
	v_dot2c_f32_bf16_e32 v199, v150, v150
	v_dot2c_f32_bf16_e32 v199, v151, v151
	v_add_u32_e32 v188, s2, v202
	v_add_u32_e32 v188, 0x10040, v188
	v_lshl_add_u64 v[148:149], v[188:189], 1, s[38:39]
	global_load_dwordx4 v[148:151], v[148:149], off
	s_waitcnt vmcnt(11)
	ds_write_b128 v212, v[144:147] offset:13824
	v_dot2c_f32_bf16_e32 v198, v144, v144
	v_dot2c_f32_bf16_e32 v198, v145, v145
	v_dot2c_f32_bf16_e32 v198, v146, v146
	v_dot2c_f32_bf16_e32 v198, v147, v147
	v_add_u32_e32 v188, s2, v202
	v_add_u32_e32 v188, 0x18040, v188
	v_lshl_add_u64 v[144:145], v[188:189], 1, s[38:39]
	global_load_dwordx4 v[144:147], v[144:145], off
	s_waitcnt vmcnt(11)
	ds_write_b128 v212, v[140:143] offset:18432
	v_dot2c_f32_bf16_e32 v197, v140, v140
	v_dot2c_f32_bf16_e32 v197, v141, v141
	v_dot2c_f32_bf16_e32 v197, v142, v142
	v_dot2c_f32_bf16_e32 v197, v143, v143
	v_add_u32_e32 v188, s2, v202
	v_add_u32_e32 v188, 0x20040, v188
	v_lshl_add_u64 v[140:141], v[188:189], 1, s[38:39]
	global_load_dwordx4 v[140:143], v[140:141], off
	s_waitcnt vmcnt(11)
	ds_write_b128 v212, v[136:139] offset:23040
	v_dot2c_f32_bf16_e32 v196, v136, v136
	v_dot2c_f32_bf16_e32 v196, v137, v137
	v_dot2c_f32_bf16_e32 v196, v138, v138
	v_dot2c_f32_bf16_e32 v196, v139, v139
	v_add_u32_e32 v188, s2, v202
	v_add_u32_e32 v188, 0x28040, v188
	v_lshl_add_u64 v[136:137], v[188:189], 1, s[38:39]
	global_load_dwordx4 v[136:139], v[136:137], off
	s_waitcnt vmcnt(11)
	ds_write_b128 v212, v[132:135] offset:27648
	v_dot2c_f32_bf16_e32 v195, v132, v132
	v_dot2c_f32_bf16_e32 v195, v133, v133
	v_dot2c_f32_bf16_e32 v195, v134, v134
	v_dot2c_f32_bf16_e32 v195, v135, v135
	v_add_u32_e32 v188, s2, v202
	v_add_u32_e32 v188, 0x30040, v188
	v_lshl_add_u64 v[132:133], v[188:189], 1, s[38:39]
	global_load_dwordx4 v[132:135], v[132:133], off
	s_waitcnt vmcnt(11)
	ds_write_b128 v212, v[128:131] offset:32256
	v_dot2c_f32_bf16_e32 v194, v128, v128
	v_dot2c_f32_bf16_e32 v194, v129, v129
	v_dot2c_f32_bf16_e32 v194, v130, v130
	v_dot2c_f32_bf16_e32 v194, v131, v131
	v_add_u32_e32 v188, s2, v202
	v_add_u32_e32 v188, 0x38040, v188
	v_lshl_add_u64 v[128:129], v[188:189], 1, s[38:39]
	global_load_dwordx4 v[128:131], v[128:129], off
	s_waitcnt lgkmcnt(0)
	s_barrier
; template <bool NORM, bool DEEP, int MTW, int KSEG, class HOOK>
; DI void gemm_core_h(const bfu* __restrict__ A, int lda, const bfu* __restrict__ Bt, int ldb, int K, int m0, int n0,
;                     f32x16 (&acc)[MTW][2], char* smem, HOOK hook) {
;     ...
;   if (DEEP) {
;     for (int kt = 0; kt < nk; kt += 2) {
;       GEMM_STEP(ra0, rb0, kt, 2)
;       GEMM_STEP(ra1, rb1, kt + 1, 2)
;     }
;   } else {
;     for (int kt = 0; kt < nk; ++kt) {
;       GEMM_STEP(ra0, rb0, kt, 1)
	ds_read_b128 v[214:217], v211 offset:36864
	ds_read_b128 v[184:187], v211 offset:41472
	ds_read_b128 v[218:221], v205
	ds_read_b128 v[238:241], v205 offset:4608
	s_waitcnt lgkmcnt(1)
	v_mfma_f32_32x32x16_bf16 v[112:127], v[218:221], v[214:217], v[112:127]
	v_mfma_f32_32x32x16_bf16 v[96:111], v[218:221], v[184:187], v[96:111]
	ds_read_b128 v[218:221], v205 offset:9216
	s_waitcnt lgkmcnt(1)
	v_mfma_f32_32x32x16_bf16 v[80:95], v[238:241], v[214:217], v[80:95]
	v_mfma_f32_32x32x16_bf16 v[64:79], v[238:241], v[184:187], v[64:79]
	ds_read_b128 v[238:241], v203
	ds_read_b128 v[176:179], v211 offset:36896
	ds_read_b128 v[180:183], v211 offset:41504
	s_waitcnt lgkmcnt(3)
	v_mfma_f32_32x32x16_bf16 v[48:63], v[218:221], v[214:217], v[48:63]
	v_mfma_f32_32x32x16_bf16 v[32:47], v[218:221], v[184:187], v[32:47]
	ds_read_b128 v[218:221], v205 offset:32
	s_waitcnt lgkmcnt(3)
	v_mfma_f32_32x32x16_bf16 v[16:31], v[238:241], v[214:217], v[16:31]
	v_mfma_f32_32x32x16_bf16 v[0:15], v[238:241], v[184:187], v[0:15]
	ds_read_b128 v[238:241], v205 offset:4640
	s_waitcnt lgkmcnt(1)
	v_mfma_f32_32x32x16_bf16 v[112:127], v[218:221], v[176:179], v[112:127]
	v_mfma_f32_32x32x16_bf16 v[96:111], v[218:221], v[180:183], v[96:111]
	ds_read_b128 v[218:221], v205 offset:9248
	s_waitcnt lgkmcnt(1)
	v_mfma_f32_32x32x16_bf16 v[80:95], v[238:241], v[176:179], v[80:95]
	v_mfma_f32_32x32x16_bf16 v[64:79], v[238:241], v[180:183], v[64:79]
	ds_read_b128 v[238:241], v203 offset:32
	ds_read_b128 v[214:217], v211 offset:36928
	ds_read_b128 v[184:187], v211 offset:41536
	s_waitcnt lgkmcnt(3)
	v_mfma_f32_32x32x16_bf16 v[48:63], v[218:221], v[176:179], v[48:63]
	v_mfma_f32_32x32x16_bf16 v[32:47], v[218:221], v[180:183], v[32:47]
	ds_read_b128 v[218:221], v205 offset:64
	s_waitcnt lgkmcnt(3)
	v_mfma_f32_32x32x16_bf16 v[16:31], v[238:241], v[176:179], v[16:31]
	v_mfma_f32_32x32x16_bf16 v[0:15], v[238:241], v[180:183], v[0:15]
	ds_read_b128 v[238:241], v205 offset:4672
	s_waitcnt lgkmcnt(1)
	v_mfma_f32_32x32x16_bf16 v[112:127], v[218:221], v[214:217], v[112:127]
	v_mfma_f32_32x32x16_bf16 v[96:111], v[218:221], v[184:187], v[96:111]
	ds_read_b128 v[218:221], v205 offset:9280
	s_waitcnt lgkmcnt(1)
	v_mfma_f32_32x32x16_bf16 v[80:95], v[238:241], v[214:217], v[80:95]
	v_mfma_f32_32x32x16_bf16 v[64:79], v[238:241], v[184:187], v[64:79]
	ds_read_b128 v[238:241], v203 offset:64
	ds_read_b128 v[176:179], v211 offset:36960
	ds_read_b128 v[180:183], v211 offset:41568
	s_waitcnt lgkmcnt(3)
	v_mfma_f32_32x32x16_bf16 v[48:63], v[218:221], v[214:217], v[48:63]
	v_mfma_f32_32x32x16_bf16 v[32:47], v[218:221], v[184:187], v[32:47]
	ds_read_b128 v[218:221], v205 offset:96
	s_waitcnt lgkmcnt(3)
	v_mfma_f32_32x32x16_bf16 v[16:31], v[238:241], v[214:217], v[16:31]
	v_mfma_f32_32x32x16_bf16 v[0:15], v[238:241], v[184:187], v[0:15]
	ds_read_b128 v[238:241], v205 offset:4704
	s_waitcnt lgkmcnt(1)
	v_mfma_f32_32x32x16_bf16 v[112:127], v[218:221], v[176:179], v[112:127]
	v_mfma_f32_32x32x16_bf16 v[96:111], v[218:221], v[180:183], v[96:111]
	ds_read_b128 v[218:221], v205 offset:9312
	s_waitcnt lgkmcnt(1)
	v_mfma_f32_32x32x16_bf16 v[80:95], v[238:241], v[176:179], v[80:95]
	v_mfma_f32_32x32x16_bf16 v[64:79], v[238:241], v[180:183], v[64:79]
	ds_read_b128 v[238:241], v203 offset:96
	s_waitcnt lgkmcnt(1)
	v_mfma_f32_32x32x16_bf16 v[48:63], v[218:221], v[176:179], v[48:63]
	v_mfma_f32_32x32x16_bf16 v[32:47], v[218:221], v[180:183], v[32:47]
	s_waitcnt lgkmcnt(0)
	v_mfma_f32_32x32x16_bf16 v[16:31], v[238:241], v[176:179], v[16:31]
	v_mfma_f32_32x32x16_bf16 v[0:15], v[238:241], v[180:183], v[0:15]
	s_add_i32 s2, s2, 64
	s_cmpk_eq_i32 s2, 0x3c0
	s_cbranch_scc0 .LBB0_782
	s_waitcnt vmcnt(0)
	s_waitcnt lgkmcnt(0)
	s_barrier
	s_waitcnt vmcnt(11)
	ds_write_b128 v212, v[156:159]
	s_waitcnt vmcnt(10)
	ds_write_b128 v212, v[152:155] offset:4608
	s_waitcnt vmcnt(9)
	ds_write_b128 v212, v[148:151] offset:9216
	s_waitcnt vmcnt(8)
	ds_write_b128 v212, v[144:147] offset:13824
	s_waitcnt vmcnt(7)
	ds_write_b128 v212, v[140:143] offset:18432
	s_waitcnt vmcnt(6)
	ds_write_b128 v212, v[136:139] offset:23040
	s_waitcnt vmcnt(5)
	ds_write_b128 v212, v[132:135] offset:27648
	s_waitcnt vmcnt(4)
	ds_write_b128 v212, v[128:131] offset:32256
	s_waitcnt vmcnt(3)
	ds_write_b128 v212, v[160:163] offset:36864
	s_waitcnt vmcnt(2)
	ds_write_b128 v212, v[164:167] offset:41472
	s_waitcnt vmcnt(1)
	ds_write_b128 v212, v[168:171] offset:46080
	s_waitcnt vmcnt(0)
	ds_write_b128 v212, v[172:175] offset:50688
	s_waitcnt lgkmcnt(0)
	s_barrier
; template <bool NORM, bool DEEP, int MTW, int KSEG, class HOOK>
; DI void gemm_core_h(const bfu* __restrict__ A, int lda, const bfu* __restrict__ Bt, int ldb, int K, int m0, int n0,
;                     f32x16 (&acc)[MTW][2], char* smem, HOOK hook) {
;     ...
;   if (DEEP) {
;     for (int kt = 0; kt < nk; kt += 2) {
;       GEMM_STEP(ra0, rb0, kt, 2)
;       GEMM_STEP(ra1, rb1, kt + 1, 2)
;     }
;   } else {
;     for (int kt = 0; kt < nk; ++kt) {
;       GEMM_STEP(ra0, rb0, kt, 1)
;       if (KSEG > 0) { if (((kt + 1) % (KSEG > 0 ? KSEG : 1)) == 0) hook((kt + 1) / (KSEG > 0 ? KSEG : 1) - 1); }
;     }
;   }
;     ...
;   if (NORM) {
; #pragma unroll
;     for (int j = 0; j < NA; ++j) {
;       float v = ssq[j];
;       v += __shfl_xor(v, 1); v += __shfl_xor(v, 2); v += __shfl_xor(v, 4);
;       if (lkc == 0) rstd_s[lrow + 32 * j] = rsqrtf(v / (float)K + EPS);
;     }
	ds_read_b128 v[160:163], v205
	ds_read_b128 v[164:167], v211 offset:36864
	ds_read_b128 v[168:171], v211 offset:41472
	s_waitcnt lgkmcnt(1)
	v_mfma_f32_32x32x16_bf16 v[112:127], v[160:163], v[164:167], v[112:127]
	s_waitcnt lgkmcnt(0)
	v_mfma_f32_32x32x16_bf16 v[96:111], v[160:163], v[168:171], v[96:111]
	ds_read_b128 v[160:163], v205 offset:4608
	s_waitcnt lgkmcnt(0)
	v_mfma_f32_32x32x16_bf16 v[80:95], v[160:163], v[164:167], v[80:95]
	v_mfma_f32_32x32x16_bf16 v[64:79], v[160:163], v[168:171], v[64:79]
	ds_read_b128 v[160:163], v205 offset:9216
	s_waitcnt lgkmcnt(0)
	v_mfma_f32_32x32x16_bf16 v[48:63], v[160:163], v[164:167], v[48:63]
	v_mfma_f32_32x32x16_bf16 v[32:47], v[160:163], v[168:171], v[32:47]
	ds_read_b128 v[160:163], v203
	s_waitcnt lgkmcnt(0)
	v_mfma_f32_32x32x16_bf16 v[16:31], v[160:163], v[164:167], v[16:31]
	v_mfma_f32_32x32x16_bf16 v[0:15], v[160:163], v[168:171], v[0:15]
	ds_read_b128 v[160:163], v205 offset:32
	ds_read_b128 v[164:167], v211 offset:36896
	ds_read_b128 v[168:171], v211 offset:41504
	s_waitcnt lgkmcnt(1)
	v_mfma_f32_32x32x16_bf16 v[112:127], v[160:163], v[164:167], v[112:127]
	s_waitcnt lgkmcnt(0)
	v_mfma_f32_32x32x16_bf16 v[96:111], v[160:163], v[168:171], v[96:111]
	ds_read_b128 v[160:163], v205 offset:4640
	s_waitcnt lgkmcnt(0)
	v_mfma_f32_32x32x16_bf16 v[80:95], v[160:163], v[164:167], v[80:95]
	v_mfma_f32_32x32x16_bf16 v[64:79], v[160:163], v[168:171], v[64:79]
	ds_read_b128 v[160:163], v205 offset:9248
	s_waitcnt lgkmcnt(0)
	v_mfma_f32_32x32x16_bf16 v[48:63], v[160:163], v[164:167], v[48:63]
	v_mfma_f32_32x32x16_bf16 v[32:47], v[160:163], v[168:171], v[32:47]
	ds_read_b128 v[160:163], v203 offset:32
	s_waitcnt lgkmcnt(0)
	v_mfma_f32_32x32x16_bf16 v[16:31], v[160:163], v[164:167], v[16:31]
	v_mfma_f32_32x32x16_bf16 v[0:15], v[160:163], v[168:171], v[0:15]
	ds_read_b128 v[160:163], v205 offset:64
	ds_read_b128 v[164:167], v211 offset:36928
	ds_read_b128 v[168:171], v211 offset:41536
	s_waitcnt lgkmcnt(1)
	v_mfma_f32_32x32x16_bf16 v[112:127], v[160:163], v[164:167], v[112:127]
	s_waitcnt lgkmcnt(0)
	v_mfma_f32_32x32x16_bf16 v[96:111], v[160:163], v[168:171], v[96:111]
	ds_read_b128 v[160:163], v205 offset:4672
	s_waitcnt lgkmcnt(0)
	v_mfma_f32_32x32x16_bf16 v[80:95], v[160:163], v[164:167], v[80:95]
	v_mfma_f32_32x32x16_bf16 v[64:79], v[160:163], v[168:171], v[64:79]
	ds_read_b128 v[160:163], v205 offset:9280
	s_waitcnt lgkmcnt(0)
	v_mfma_f32_32x32x16_bf16 v[48:63], v[160:163], v[164:167], v[48:63]
	v_mfma_f32_32x32x16_bf16 v[32:47], v[160:163], v[168:171], v[32:47]
	ds_read_b128 v[160:163], v203 offset:64
	s_waitcnt lgkmcnt(0)
	v_mfma_f32_32x32x16_bf16 v[16:31], v[160:163], v[164:167], v[16:31]
	v_mfma_f32_32x32x16_bf16 v[0:15], v[160:163], v[168:171], v[0:15]
	ds_read_b128 v[168:171], v205 offset:96
	ds_read_b128 v[164:167], v211 offset:36960
	ds_read_b128 v[160:163], v211 offset:41568
	ds_read_b128 v[172:175], v205 offset:4704
	s_waitcnt lgkmcnt(2)
	v_mfma_f32_32x32x16_bf16 v[112:127], v[168:171], v[164:167], v[112:127]
	s_waitcnt lgkmcnt(1)
	v_mfma_f32_32x32x16_bf16 v[96:111], v[168:171], v[160:163], v[96:111]
	v_lshlrev_b32_e32 v168, 16, v156
	v_and_b32_e32 v156, 0xffff0000, v156
	v_mul_f32_e32 v156, v156, v156
	v_fmac_f32_e32 v156, v168, v168
	v_lshlrev_b32_e32 v168, 16, v157
	v_and_b32_e32 v157, 0xffff0000, v157
	v_mul_f32_e32 v157, v157, v157
	v_add_f32_e32 v156, v201, v156
	v_fmac_f32_e32 v157, v168, v168
	v_add_f32_e32 v156, v157, v156
	v_lshlrev_b32_e32 v157, 16, v158
	v_and_b32_e32 v158, 0xffff0000, v158
	v_mul_f32_e32 v158, v158, v158
	ds_read_b128 v[168:171], v205 offset:9312
	v_fmac_f32_e32 v158, v157, v157
	v_add_f32_e32 v156, v158, v156
	v_and_b32_e32 v158, 0xffff0000, v159
	v_lshlrev_b32_e32 v157, 16, v159
	v_mul_f32_e32 v158, v158, v158
	v_fmac_f32_e32 v158, v157, v157
	v_and_b32_e32 v157, 64, v227
	s_waitcnt lgkmcnt(1)
	v_mfma_f32_32x32x16_bf16 v[80:95], v[172:175], v[164:167], v[80:95]
	v_add_f32_e32 v158, v158, v156
	v_xor_b32_e32 v156, 1, v227
	v_add_u32_e32 v159, 64, v157
	v_cmp_lt_i32_e32 vcc, v156, v159
	v_xor_b32_e32 v157, 2, v227
	s_nop 0
	v_cndmask_b32_e32 v156, v227, v156, vcc
	v_mfma_f32_32x32x16_bf16 v[64:79], v[172:175], v[160:163], v[64:79]
	ds_read_b128 v[172:175], v203 offset:96
	v_lshlrev_b32_e32 v156, 2, v156
	v_cmp_lt_i32_e32 vcc, v157, v159
	s_nop 1
	v_cndmask_b32_e32 v157, v227, v157, vcc
	v_lshlrev_b32_e32 v157, 2, v157
	s_waitcnt lgkmcnt(1)
	v_mfma_f32_32x32x16_bf16 v[48:63], v[168:171], v[164:167], v[48:63]
	v_mfma_f32_32x32x16_bf16 v[32:47], v[168:171], v[160:163], v[32:47]
	ds_bpermute_b32 v168, v156, v158
	v_xor_b32_e32 v169, 4, v227
	v_cmp_lt_i32_e32 vcc, v169, v159
	s_waitcnt lgkmcnt(1)
	v_mfma_f32_32x32x16_bf16 v[16:31], v[172:175], v[164:167], v[16:31]
	s_waitcnt lgkmcnt(0)
	v_add_f32_e32 v164, v158, v168
	ds_bpermute_b32 v165, v157, v164
	v_cndmask_b32_e32 v158, v227, v169, vcc
	v_lshlrev_b32_e32 v159, 2, v158
	v_cmp_eq_u32_e32 vcc, 0, v210
	v_lshlrev_b32_e32 v158, 2, v193
	s_waitcnt lgkmcnt(0)
	v_add_f32_e32 v164, v164, v165
	v_mfma_f32_32x32x16_bf16 v[0:15], v[172:175], v[160:163], v[0:15]
	ds_bpermute_b32 v165, v159, v164
	s_and_saveexec_b64 s[4:5], vcc
	s_cbranch_execz .LBB0_785
	s_waitcnt lgkmcnt(0)
	v_add_f32_e32 v160, v164, v165
	v_fmamk_f32 v160, v160, 0x3a800000, v225
	s_mov_b32 s2, 0x800000
	v_mul_f32_e32 v161, 0x4b800000, v160
	v_cmp_gt_f32_e64 s[2:3], s2, v160
	s_nop 1
	v_cndmask_b32_e64 v160, v160, v161, s[2:3]
	v_rsq_f32_e32 v160, v160
	s_nop 0
	v_mul_f32_e32 v161, 0x45800000, v160
	v_cndmask_b32_e64 v160, v160, v161, s[2:3]
	ds_write_b32 v158, v160 offset:55296
